# GLA scan: next batch of chunk operands warmed in L2 by register-free dummy LDS-DMA loads (counted waits adjusted); plus previous edits
# baseline (speedup 1.0000x reference)
; #define GAS __attribute__((address_space(1)))
; DI void gla_scan_wave(const Frame& F, int item) {
;     ...
;     for (int c0 = 0; c0 < NCH; c0 += U) {
;         f32x4 e[U], g[U];
; #pragma unroll
;         for (int u = 0; u < U; ++u) { const unsigned char* gk = gk_ptr(F, c0 + u, h); e[u] = *(const GAS f32x4*)(gk + GK_E + (size_t)((vs * 4 + mt) * 64 + lane) * 16); g[u] = *(const GAS f32x4*)(gk + GK_GC + (16 * mt + 4 * g4) * 4); }
.LBB0_804:
	v_lshl_add_u64 v[0:1], s[4:5], 0, v[184:185]
	s_mov_b64 s[98:99], 0x3c5000
	v_lshl_add_u64 v[142:143], v[0:1], 0, s[98:99]
	v_add_co_u32_e32 v2, vcc, 0x52568000, v0
	v_lshl_add_u64 v[4:5], s[4:5], 0, v[124:125]
	v_lshl_add_u64 v[144:145], v[4:5], 0, s[98:99]
	s_nop 0
	v_addc_co_u32_e32 v3, vcc, 0, v1, vcc
	v_add_co_u32_e32 v6, vcc, 0x52574000, v4
	s_nop 1
	v_addc_co_u32_e32 v7, vcc, 0, v5, vcc
	global_load_dwordx4 v[120:123], v[2:3], off
	global_load_dwordx4 v[138:141], v[6:7], off
	v_add_co_u32_e32 v2, vcc, 0x525a4000, v0
	s_nop 1
	v_addc_co_u32_e32 v3, vcc, 0, v1, vcc
	v_add_co_u32_e32 v6, vcc, 0x525b0000, v4
	s_nop 1
	v_addc_co_u32_e32 v7, vcc, 0, v5, vcc
	global_load_dwordx4 v[108:111], v[2:3], off offset:1280
	global_load_dwordx4 v[116:119], v[6:7], off offset:1280
	v_add_co_u32_e32 v2, vcc, 0x525e0000, v0
	s_nop 1
	v_addc_co_u32_e32 v3, vcc, 0, v1, vcc
	v_add_co_u32_e32 v6, vcc, 0x525ec000, v4
	s_nop 1
	v_addc_co_u32_e32 v7, vcc, 0, v5, vcc
	global_load_dwordx4 v[104:107], v[2:3], off offset:2560
	global_load_dwordx4 v[112:115], v[6:7], off offset:2560
	v_add_co_u32_e32 v2, vcc, 0x5261c000, v0
	s_nop 1
	v_addc_co_u32_e32 v3, vcc, 0, v1, vcc
	v_add_co_u32_e32 v6, vcc, 0x52628000, v4
	s_nop 1
	v_addc_co_u32_e32 v7, vcc, 0, v5, vcc
	global_load_dwordx4 v[96:99], v[2:3], off offset:3840
	global_load_dwordx4 v[100:103], v[6:7], off offset:3840
	v_add_co_u32_e32 v2, vcc, 0x52659000, v0
	s_nop 1
	v_addc_co_u32_e32 v3, vcc, 0, v1, vcc
	v_add_co_u32_e32 v6, vcc, 0x52665000, v4
	s_nop 1
	v_addc_co_u32_e32 v7, vcc, 0, v5, vcc
	global_load_dwordx4 v[88:91], v[2:3], off offset:1024
	global_load_dwordx4 v[92:95], v[6:7], off offset:1024
	v_add_co_u32_e32 v2, vcc, 0x52695000, v0
	s_nop 1
	v_addc_co_u32_e32 v3, vcc, 0, v1, vcc
	v_add_co_u32_e32 v6, vcc, 0x526a1000, v4
	s_nop 1
	v_addc_co_u32_e32 v7, vcc, 0, v5, vcc
	global_load_dwordx4 v[80:83], v[2:3], off offset:2304
	global_load_dwordx4 v[84:87], v[6:7], off offset:2304
	v_add_co_u32_e32 v2, vcc, 0x526d1000, v0
	s_nop 1
	v_addc_co_u32_e32 v3, vcc, 0, v1, vcc
	v_add_co_u32_e32 v6, vcc, 0x526dd000, v4
	s_nop 1
	v_addc_co_u32_e32 v7, vcc, 0, v5, vcc
	global_load_dwordx4 v[72:75], v[2:3], off offset:3584
	global_load_dwordx4 v[76:79], v[6:7], off offset:3584
	v_add_co_u32_e32 v2, vcc, 0x5270e000, v0
	s_nop 1
	v_addc_co_u32_e32 v3, vcc, 0, v1, vcc
	v_add_co_u32_e32 v6, vcc, 0x5271a000, v4
	s_nop 1
	v_addc_co_u32_e32 v7, vcc, 0, v5, vcc
	global_load_dwordx4 v[64:67], v[2:3], off offset:768
	global_load_dwordx4 v[68:71], v[6:7], off offset:768
	v_add_co_u32_e32 v2, vcc, 0x5274a000, v0
	s_nop 1
	v_addc_co_u32_e32 v3, vcc, 0, v1, vcc
	v_add_co_u32_e32 v6, vcc, 0x52756000, v4
	s_nop 1
	v_addc_co_u32_e32 v7, vcc, 0, v5, vcc
	global_load_dwordx4 v[56:59], v[2:3], off offset:2048
	global_load_dwordx4 v[60:63], v[6:7], off offset:2048
	v_add_co_u32_e32 v2, vcc, 0x52786000, v0
	s_nop 1
	v_addc_co_u32_e32 v3, vcc, 0, v1, vcc
	v_add_co_u32_e32 v6, vcc, 0x52792000, v4
	s_nop 1
	v_addc_co_u32_e32 v7, vcc, 0, v5, vcc
	global_load_dwordx4 v[48:51], v[2:3], off offset:3328
	global_load_dwordx4 v[52:55], v[6:7], off offset:3328
	v_add_co_u32_e32 v2, vcc, 0x527c3000, v0
	s_nop 1
	v_addc_co_u32_e32 v3, vcc, 0, v1, vcc
	v_add_co_u32_e32 v6, vcc, 0x527cf000, v4
	s_nop 1
	v_addc_co_u32_e32 v7, vcc, 0, v5, vcc
	global_load_dwordx4 v[40:43], v[2:3], off offset:512
	global_load_dwordx4 v[44:47], v[6:7], off offset:512
	v_add_co_u32_e32 v2, vcc, 0x527ff000, v0
	s_nop 1
	v_addc_co_u32_e32 v3, vcc, 0, v1, vcc
	v_add_co_u32_e32 v6, vcc, 0x5280b000, v4
	s_nop 1
	v_addc_co_u32_e32 v7, vcc, 0, v5, vcc
	global_load_dwordx4 v[32:35], v[2:3], off offset:1792
	global_load_dwordx4 v[36:39], v[6:7], off offset:1792
	v_add_co_u32_e32 v2, vcc, 0x5283b000, v0
	s_nop 1
	v_addc_co_u32_e32 v3, vcc, 0, v1, vcc
	v_add_co_u32_e32 v6, vcc, 0x52847000, v4
	s_nop 1
	v_addc_co_u32_e32 v7, vcc, 0, v5, vcc
	global_load_dwordx4 v[24:27], v[2:3], off offset:3072
	global_load_dwordx4 v[28:31], v[6:7], off offset:3072
	v_add_co_u32_e32 v2, vcc, 0x52878000, v0
	s_nop 1
	v_addc_co_u32_e32 v3, vcc, 0, v1, vcc
	v_add_co_u32_e32 v6, vcc, 0x52884000, v4
	s_nop 1
	v_addc_co_u32_e32 v7, vcc, 0, v5, vcc
	global_load_dwordx4 v[16:19], v[2:3], off offset:256
	global_load_dwordx4 v[20:23], v[6:7], off offset:256
	v_add_co_u32_e32 v2, vcc, 0x528b4000, v0
	s_nop 1
	v_addc_co_u32_e32 v3, vcc, 0, v1, vcc
	v_add_co_u32_e32 v6, vcc, 0x528c0000, v4
	s_nop 1
	v_addc_co_u32_e32 v7, vcc, 0, v5, vcc
	v_add_co_u32_e32 v0, vcc, 0x528f0000, v0
	global_load_dwordx4 v[8:11], v[2:3], off offset:1536
	global_load_dwordx4 v[12:15], v[6:7], off offset:1536
	v_addc_co_u32_e32 v1, vcc, 0, v1, vcc
	v_add_co_u32_e32 v4, vcc, 0x528fc000, v4
	s_nop 1
	v_addc_co_u32_e32 v5, vcc, 0, v5, vcc
	global_load_dwordx4 v[0:3], v[0:1], off offset:2816
	s_nop 0
	global_load_dwordx4 v[4:7], v[4:5], off offset:2816
	s_mov_b32 m0, 0
	s_mov_b64 s[100:101], 0x52568000
	v_lshl_add_u64 v[146:147], v[142:143], 0, s[100:101]
	global_load_lds_dword v[146:147], off
	s_mov_b64 s[100:101], 0x52574000
	v_lshl_add_u64 v[148:149], v[144:145], 0, s[100:101]
	global_load_lds_dword v[148:149], off
	s_mov_b64 s[100:101], 0x525a4000
	v_lshl_add_u64 v[146:147], v[142:143], 0, s[100:101]
	global_load_lds_dword v[146:147], off offset:1280
	s_mov_b64 s[100:101], 0x525b0000
	v_lshl_add_u64 v[148:149], v[144:145], 0, s[100:101]
	global_load_lds_dword v[148:149], off offset:1280
	s_mov_b64 s[100:101], 0x525e0000
	v_lshl_add_u64 v[146:147], v[142:143], 0, s[100:101]
	global_load_lds_dword v[146:147], off offset:2560
	s_mov_b64 s[100:101], 0x525ec000
	v_lshl_add_u64 v[148:149], v[144:145], 0, s[100:101]
; #define GAS __attribute__((address_space(1)))
; DI unsigned pk2(float lo, float hi) { f32x2 v = {lo, hi}; bf16x2_t r = __builtin_convertvector(v, bf16x2_t); return __builtin_bit_cast(unsigned, r); }
; #define SB() __builtin_amdgcn_sched_barrier(0)
; DI void gla_scan_wave(const Frame& F, int item) {
;     ...
;     for (int c0 = 0; c0 < NCH; c0 += U) {
;         f32x4 e[U], g[U];
; #pragma unroll
;         for (int u = 0; u < U; ++u) { const unsigned char* gk = gk_ptr(F, c0 + u, h); e[u] = *(const GAS f32x4*)(gk + GK_E + (size_t)((vs * 4 + mt) * 64 + lane) * 16); g[u] = *(const GAS f32x4*)(gk + GK_GC + (16 * mt + 4 * g4) * 4); }
;         SB();
; #pragma unroll
;         for (int u = 0; u < U; ++u) { unsigned char* gk = gk_ptr(F, c0 + u, h);
;             u32x2 o; o.x = pk2(H[0], H[1]); o.y = pk2(H[2], H[3]);
;             *(GAS u32x2*)(gk + GK_H + (size_t)((vs * 2 + (mt >> 1)) * 64 + lane) * 16 + (mt & 1) * 8) = o;
;             H = g[u] * H + e[u]; }
	global_load_lds_dword v[148:149], off offset:2560
	s_mov_b64 s[100:101], 0x5261c000
	v_lshl_add_u64 v[146:147], v[142:143], 0, s[100:101]
	global_load_lds_dword v[146:147], off offset:3840
	s_mov_b64 s[100:101], 0x52628000
	v_lshl_add_u64 v[148:149], v[144:145], 0, s[100:101]
	global_load_lds_dword v[148:149], off offset:3840
	s_mov_b64 s[100:101], 0x52659000
	v_lshl_add_u64 v[146:147], v[142:143], 0, s[100:101]
	global_load_lds_dword v[146:147], off offset:1024
	s_mov_b64 s[100:101], 0x52665000
	v_lshl_add_u64 v[148:149], v[144:145], 0, s[100:101]
	global_load_lds_dword v[148:149], off offset:1024
	s_mov_b64 s[100:101], 0x52695000
	v_lshl_add_u64 v[146:147], v[142:143], 0, s[100:101]
	global_load_lds_dword v[146:147], off offset:2304
	s_mov_b64 s[100:101], 0x526a1000
	v_lshl_add_u64 v[148:149], v[144:145], 0, s[100:101]
	global_load_lds_dword v[148:149], off offset:2304
	s_mov_b64 s[100:101], 0x526d1000
	v_lshl_add_u64 v[146:147], v[142:143], 0, s[100:101]
	global_load_lds_dword v[146:147], off offset:3584
	s_mov_b64 s[100:101], 0x526dd000
	v_lshl_add_u64 v[148:149], v[144:145], 0, s[100:101]
	global_load_lds_dword v[148:149], off offset:3584
	s_mov_b64 s[100:101], 0x5270e000
	v_lshl_add_u64 v[146:147], v[142:143], 0, s[100:101]
	global_load_lds_dword v[146:147], off offset:768
	s_mov_b64 s[100:101], 0x5271a000
	v_lshl_add_u64 v[148:149], v[144:145], 0, s[100:101]
	global_load_lds_dword v[148:149], off offset:768
	s_mov_b64 s[100:101], 0x5274a000
	v_lshl_add_u64 v[146:147], v[142:143], 0, s[100:101]
	global_load_lds_dword v[146:147], off offset:2048
	s_mov_b64 s[100:101], 0x52756000
	v_lshl_add_u64 v[148:149], v[144:145], 0, s[100:101]
	global_load_lds_dword v[148:149], off offset:2048
	s_mov_b64 s[100:101], 0x52786000
	v_lshl_add_u64 v[146:147], v[142:143], 0, s[100:101]
	global_load_lds_dword v[146:147], off offset:3328
	s_mov_b64 s[100:101], 0x52792000
	v_lshl_add_u64 v[148:149], v[144:145], 0, s[100:101]
	global_load_lds_dword v[148:149], off offset:3328
	s_mov_b64 s[100:101], 0x527c3000
	v_lshl_add_u64 v[146:147], v[142:143], 0, s[100:101]
	global_load_lds_dword v[146:147], off offset:512
	s_mov_b64 s[100:101], 0x527cf000
	v_lshl_add_u64 v[148:149], v[144:145], 0, s[100:101]
	global_load_lds_dword v[148:149], off offset:512
	s_mov_b64 s[100:101], 0x527ff000
	v_lshl_add_u64 v[146:147], v[142:143], 0, s[100:101]
	global_load_lds_dword v[146:147], off offset:1792
	s_mov_b64 s[100:101], 0x5280b000
	v_lshl_add_u64 v[148:149], v[144:145], 0, s[100:101]
	global_load_lds_dword v[148:149], off offset:1792
	s_mov_b64 s[100:101], 0x5283b000
	v_lshl_add_u64 v[146:147], v[142:143], 0, s[100:101]
	global_load_lds_dword v[146:147], off offset:3072
	s_mov_b64 s[100:101], 0x52847000
	v_lshl_add_u64 v[148:149], v[144:145], 0, s[100:101]
	global_load_lds_dword v[148:149], off offset:3072
	s_mov_b64 s[100:101], 0x52878000
	v_lshl_add_u64 v[146:147], v[142:143], 0, s[100:101]
	global_load_lds_dword v[146:147], off offset:256
	s_mov_b64 s[100:101], 0x52884000
	v_lshl_add_u64 v[148:149], v[144:145], 0, s[100:101]
	global_load_lds_dword v[148:149], off offset:256
	s_mov_b64 s[100:101], 0x528b4000
	v_lshl_add_u64 v[146:147], v[142:143], 0, s[100:101]
	global_load_lds_dword v[146:147], off offset:1536
	s_mov_b64 s[100:101], 0x528c0000
	v_lshl_add_u64 v[148:149], v[144:145], 0, s[100:101]
	global_load_lds_dword v[148:149], off offset:1536
	s_mov_b64 s[100:101], 0x528f0000
	v_lshl_add_u64 v[146:147], v[142:143], 0, s[100:101]
	global_load_lds_dword v[146:147], off offset:2816
	s_mov_b64 s[100:101], 0x528fc000
	v_lshl_add_u64 v[148:149], v[144:145], 0, s[100:101]
	global_load_lds_dword v[148:149], off offset:2816
	v_lshl_add_u64 v[130:131], s[4:5], 0, v[126:127]
	s_mov_b32 s1, 0x52570000
	v_cvt_pk_bf16_f32 v136, v132, v133
	s_waitcnt vmcnt(62)
	v_pk_fma_f32 v[120:121], v[132:133], v[138:139], v[120:121]
	v_add_co_u32_e32 v132, vcc, s1, v130
	s_mov_b32 s1, 0x525ac000
	s_nop 0
	v_addc_co_u32_e32 v133, vcc, 0, v131, vcc
	s_waitcnt vmcnt(60)
	v_pk_fma_f32 v[108:109], v[120:121], v[116:117], v[108:109]
	v_add_co_u32_e32 v116, vcc, s1, v130
	v_pk_fma_f32 v[122:123], v[134:135], v[140:141], v[122:123]
	s_nop 0
	v_addc_co_u32_e32 v117, vcc, 0, v131, vcc
	s_mov_b32 s1, 0x525e8000
	v_pk_fma_f32 v[110:111], v[122:123], v[118:119], v[110:111]
	v_cvt_pk_bf16_f32 v118, v108, v109
	s_waitcnt vmcnt(58)
	v_pk_fma_f32 v[104:105], v[108:109], v[112:113], v[104:105]
	v_add_co_u32_e32 v108, vcc, s1, v130
	s_mov_b32 s1, 0x52624000
	s_nop 0
	v_addc_co_u32_e32 v109, vcc, 0, v131, vcc
	s_waitcnt vmcnt(56)
	v_pk_fma_f32 v[96:97], v[104:105], v[100:101], v[96:97]
	v_add_co_u32_e32 v100, vcc, s1, v130
	s_mov_b32 s1, 0x52661000
	s_nop 0
	v_addc_co_u32_e32 v101, vcc, 0, v131, vcc
	s_waitcnt vmcnt(54)
	v_pk_fma_f32 v[88:89], v[96:97], v[92:93], v[88:89]
	v_add_co_u32_e32 v92, vcc, s1, v130
	s_mov_b32 s1, 0x5269d000
	s_nop 0
	v_addc_co_u32_e32 v93, vcc, 0, v131, vcc
	s_waitcnt vmcnt(52)
; #define GAS __attribute__((address_space(1)))
; DI unsigned pk2(float lo, float hi) { f32x2 v = {lo, hi}; bf16x2_t r = __builtin_convertvector(v, bf16x2_t); return __builtin_bit_cast(unsigned, r); }
; DI void gla_scan_wave(const Frame& F, int item) {
;     ...
; #pragma unroll
;         for (int u = 0; u < U; ++u) { unsigned char* gk = gk_ptr(F, c0 + u, h);
;             u32x2 o; o.x = pk2(H[0], H[1]); o.y = pk2(H[2], H[3]);
;             *(GAS u32x2*)(gk + GK_H + (size_t)((vs * 2 + (mt >> 1)) * 64 + lane) * 16 + (mt & 1) * 8) = o;
;             H = g[u] * H + e[u]; }
;     }
	v_pk_fma_f32 v[80:81], v[88:89], v[84:85], v[80:81]
	v_add_co_u32_e32 v84, vcc, s1, v130
	s_mov_b32 s1, 0x526d9000
	s_nop 0
	v_addc_co_u32_e32 v85, vcc, 0, v131, vcc
	s_waitcnt vmcnt(50)
	v_pk_fma_f32 v[72:73], v[80:81], v[76:77], v[72:73]
	v_add_co_u32_e32 v76, vcc, s1, v130
	s_mov_b32 s1, 0x52716000
	s_nop 0
	v_addc_co_u32_e32 v77, vcc, 0, v131, vcc
	s_waitcnt vmcnt(48)
	v_pk_fma_f32 v[64:65], v[72:73], v[68:69], v[64:65]
	v_add_co_u32_e32 v68, vcc, s1, v130
	s_mov_b32 s1, 0x52752000
	s_nop 0
	v_addc_co_u32_e32 v69, vcc, 0, v131, vcc
	s_waitcnt vmcnt(46)
	v_pk_fma_f32 v[56:57], v[64:65], v[60:61], v[56:57]
	v_add_co_u32_e32 v60, vcc, s1, v130
	s_mov_b32 s1, 0x5278e000
	s_nop 0
	v_addc_co_u32_e32 v61, vcc, 0, v131, vcc
	v_pk_fma_f32 v[106:107], v[110:111], v[114:115], v[106:107]
	s_waitcnt vmcnt(44)
	v_pk_fma_f32 v[48:49], v[56:57], v[52:53], v[48:49]
	v_add_co_u32_e32 v52, vcc, s1, v130
	v_pk_fma_f32 v[98:99], v[106:107], v[102:103], v[98:99]
	s_nop 0
	v_addc_co_u32_e32 v53, vcc, 0, v131, vcc
	s_mov_b32 s1, 0x527cb000
	v_pk_fma_f32 v[90:91], v[98:99], v[94:95], v[90:91]
	s_waitcnt vmcnt(42)
	v_pk_fma_f32 v[40:41], v[48:49], v[44:45], v[40:41]
	v_add_co_u32_e32 v44, vcc, s1, v130
	v_pk_fma_f32 v[82:83], v[90:91], v[86:87], v[82:83]
	s_nop 0
	v_addc_co_u32_e32 v45, vcc, 0, v131, vcc
	s_mov_b32 s1, 0x52807000
	v_pk_fma_f32 v[74:75], v[82:83], v[78:79], v[74:75]
	s_waitcnt vmcnt(40)
	v_pk_fma_f32 v[32:33], v[40:41], v[36:37], v[32:33]
	v_add_co_u32_e32 v36, vcc, s1, v130
	v_pk_fma_f32 v[66:67], v[74:75], v[70:71], v[66:67]
	s_nop 0
	v_addc_co_u32_e32 v37, vcc, 0, v131, vcc
	s_mov_b32 s1, 0x52843000
	v_pk_fma_f32 v[58:59], v[66:67], v[62:63], v[58:59]
	s_waitcnt vmcnt(38)
	v_pk_fma_f32 v[24:25], v[32:33], v[28:29], v[24:25]
	v_add_co_u32_e32 v28, vcc, s1, v130
	v_pk_fma_f32 v[50:51], v[58:59], v[54:55], v[50:51]
	s_nop 0
	v_addc_co_u32_e32 v29, vcc, 0, v131, vcc
	s_mov_b32 s1, 0x52880000
	v_pk_fma_f32 v[42:43], v[50:51], v[46:47], v[42:43]
	s_waitcnt vmcnt(36)
	v_pk_fma_f32 v[16:17], v[24:25], v[20:21], v[16:17]
	v_add_co_u32_e32 v20, vcc, s1, v130
	v_pk_fma_f32 v[34:35], v[42:43], v[38:39], v[34:35]
	s_nop 0
	v_addc_co_u32_e32 v21, vcc, 0, v131, vcc
	s_mov_b32 s1, 0x528bc000
	s_add_i32 s0, s0, 16
	v_pk_fma_f32 v[26:27], v[34:35], v[30:31], v[26:27]
	s_waitcnt vmcnt(34)
	v_pk_fma_f32 v[8:9], v[16:17], v[12:13], v[8:9]
	v_add_co_u32_e32 v12, vcc, s1, v130
	v_cvt_pk_bf16_f32 v137, v134, v135
	s_add_u32 s4, s4, 0x3c5000
	v_pk_fma_f32 v[18:19], v[26:27], v[22:23], v[18:19]
	v_addc_co_u32_e32 v13, vcc, 0, v131, vcc
	s_mov_b32 s1, 0x528f8000
	v_cvt_pk_bf16_f32 v134, v120, v121
	v_cvt_pk_bf16_f32 v135, v122, v123
	s_addc_u32 s5, s5, 0
	global_store_dwordx2 v[132:133], v[136:137], off
	v_pk_fma_f32 v[10:11], v[18:19], v[14:15], v[10:11]
	s_waitcnt vmcnt(33)
	v_pk_fma_f32 v[132:133], v[8:9], v[4:5], v[0:1]
	v_add_co_u32_e32 v0, vcc, s1, v130
	v_cvt_pk_bf16_f32 v119, v110, v111
	v_cvt_pk_bf16_f32 v110, v104, v105
	v_cvt_pk_bf16_f32 v111, v106, v107
	s_cmpk_gt_u32 s0, 0xef
	global_store_dwordx2 v[116:117], v[134:135], off offset:1280
	v_cvt_pk_bf16_f32 v102, v96, v97
	v_cvt_pk_bf16_f32 v103, v98, v99
	v_cvt_pk_bf16_f32 v94, v88, v89
	v_cvt_pk_bf16_f32 v95, v90, v91
	v_cvt_pk_bf16_f32 v86, v80, v81
	v_cvt_pk_bf16_f32 v87, v82, v83
	v_cvt_pk_bf16_f32 v78, v72, v73
	v_cvt_pk_bf16_f32 v79, v74, v75
	v_cvt_pk_bf16_f32 v70, v64, v65
	v_cvt_pk_bf16_f32 v71, v66, v67
	v_cvt_pk_bf16_f32 v62, v56, v57
	v_cvt_pk_bf16_f32 v63, v58, v59
	v_cvt_pk_bf16_f32 v54, v48, v49
	v_cvt_pk_bf16_f32 v55, v50, v51
	v_cvt_pk_bf16_f32 v46, v40, v41
	v_cvt_pk_bf16_f32 v47, v42, v43
	v_cvt_pk_bf16_f32 v38, v32, v33
	v_cvt_pk_bf16_f32 v39, v34, v35
	v_cvt_pk_bf16_f32 v30, v24, v25
	v_cvt_pk_bf16_f32 v31, v26, v27
	v_cvt_pk_bf16_f32 v22, v16, v17
	v_cvt_pk_bf16_f32 v23, v18, v19
	v_cvt_pk_bf16_f32 v14, v8, v9
	v_cvt_pk_bf16_f32 v15, v10, v11
	v_pk_fma_f32 v[134:135], v[10:11], v[6:7], v[2:3]
	v_addc_co_u32_e32 v1, vcc, 0, v131, vcc
	global_store_dwordx2 v[108:109], v[118:119], off offset:2560
	global_store_dwordx2 v[100:101], v[110:111], off offset:3840
	global_store_dwordx2 v[92:93], v[102:103], off offset:1024
	global_store_dwordx2 v[84:85], v[94:95], off offset:2304
	global_store_dwordx2 v[76:77], v[86:87], off offset:3584
	global_store_dwordx2 v[68:69], v[78:79], off offset:768
	global_store_dwordx2 v[60:61], v[70:71], off offset:2048
	global_store_dwordx2 v[52:53], v[62:63], off offset:3328
	global_store_dwordx2 v[44:45], v[54:55], off offset:512
	global_store_dwordx2 v[36:37], v[46:47], off offset:1792
	global_store_dwordx2 v[28:29], v[38:39], off offset:3072
	global_store_dwordx2 v[20:21], v[30:31], off offset:256
	global_store_dwordx2 v[12:13], v[22:23], off offset:1536
	global_store_dwordx2 v[0:1], v[14:15], off offset:2816
	s_cbranch_scc0 .LBB0_804
